# diff attention epilogue rewritten by hand: batched LDS reads, DPP row reductions, gains loaded once, 16-byte row stores via LDS
# speedup vs baseline: 1.0091x; 1.0023x over previous
; __device__ __forceinline__ int crow(int r, int hi) { return (r & 3) + 8 * (r >> 2) + 4 * hi; }
; template <int MODE, int ORD> ...
;     ...
;     if (cst == 0) {
;       float ssq[16];
; #pragma unroll
;       for (int r = 0; r < 16; ++r) { const int orow = crow(r, hi); float s = 0.f;
; #pragma unroll
;         for (int d0 = 0; d0 < 4; ++d0) { const float v = o[d0][r] * rli[r] - lam * X[orow * 128 + d0 * 32 + r32]; o[d0][r] = v; s = fmaf(v, v, s); }
;         ssq[r] = s; }
;     ...
;       for (int d0 = 0; d0 < 4; ++d0) gg[d0] = subg[d0 * 32 + r32] * oscale;
.LBB0_203:
	s_cmpk_gt_u32 s63, 0xff
	s_waitcnt lgkmcnt(0)
	s_barrier
	s_cbranch_scc1 .LBB0_148
	s_lshl_b64 s[0:1], s[6:7], 12
	s_add_u32 s0, s33, s0
	s_addc_u32 s1, s3, s1
	s_lshl_b32 s6, s48, 1
	s_add_u32 s0, s0, s6
	s_addc_u32 s1, s1, 0
	s_lshl_b32 s6, s62, 17
	s_add_u32 s0, s0, s6
	s_addc_u32 s1, s1, 0
	v_lshlrev_b32_e32 v168, 2, v184
	global_load_dword v164, v168, s[4:5]
	global_load_dword v165, v168, s[4:5] offset:128
	global_load_dword v166, v168, s[4:5] offset:256
	global_load_dword v167, v168, s[4:5] offset:384
	v_add_u32_e32 v169, 0x400, v70
	v_add_u32_e32 v170, 0x1000, v70
	v_add_u32_e32 v171, 0x1400, v70
	v_add_u32_e32 v172, 0x2000, v70
	v_add_u32_e32 v173, 0x2400, v70
	v_add_u32_e32 v174, 0x3000, v70
	v_add_u32_e32 v175, 0x3400, v70
	ds_read2_b32 v[84:85], v70 offset0:0 offset1:32
	ds_read2_b32 v[86:87], v70 offset0:64 offset1:96
	ds_read2_b32 v[88:89], v70 offset0:128 offset1:160
	ds_read2_b32 v[90:91], v70 offset0:192 offset1:224
	ds_read2_b32 v[92:93], v169 offset0:0 offset1:32
	ds_read2_b32 v[94:95], v169 offset0:64 offset1:96
	ds_read2_b32 v[96:97], v169 offset0:128 offset1:160
	ds_read2_b32 v[98:99], v169 offset0:192 offset1:224
	ds_read2_b32 v[100:101], v170 offset0:0 offset1:32
	ds_read2_b32 v[102:103], v170 offset0:64 offset1:96
	ds_read2_b32 v[104:105], v170 offset0:128 offset1:160
	ds_read2_b32 v[106:107], v170 offset0:192 offset1:224
	ds_read2_b32 v[108:109], v171 offset0:0 offset1:32
	ds_read2_b32 v[110:111], v171 offset0:64 offset1:96
	ds_read2_b32 v[112:113], v171 offset0:128 offset1:160
	ds_read2_b32 v[114:115], v171 offset0:192 offset1:224
	ds_read2_b32 v[116:117], v172 offset0:0 offset1:32
	ds_read2_b32 v[118:119], v172 offset0:64 offset1:96
	ds_read2_b32 v[120:121], v172 offset0:128 offset1:160
	ds_read2_b32 v[122:123], v172 offset0:192 offset1:224
	ds_read2_b32 v[124:125], v173 offset0:0 offset1:32
	ds_read2_b32 v[126:127], v173 offset0:64 offset1:96
	ds_read2_b32 v[128:129], v173 offset0:128 offset1:160
	ds_read2_b32 v[130:131], v173 offset0:192 offset1:224
	ds_read2_b32 v[132:133], v174 offset0:0 offset1:32
	ds_read2_b32 v[134:135], v174 offset0:64 offset1:96
	ds_read2_b32 v[136:137], v174 offset0:128 offset1:160
	ds_read2_b32 v[138:139], v174 offset0:192 offset1:224
	ds_read2_b32 v[140:141], v175 offset0:0 offset1:32
	ds_read2_b32 v[142:143], v175 offset0:64 offset1:96
	ds_read2_b32 v[144:145], v175 offset0:128 offset1:160
	ds_read2_b32 v[146:147], v175 offset0:192 offset1:224
	s_waitcnt lgkmcnt(0)
	v_mul_f32_e32 v84, s60, v84
	v_mul_f32_e32 v85, s60, v85
	v_mul_f32_e32 v86, s60, v86
	v_mul_f32_e32 v87, s60, v87
	v_fma_f32 v0, v0, v66, -v84
	v_fma_f32 v48, v48, v66, -v85
	v_fma_f32 v32, v32, v66, -v86
	v_fma_f32 v16, v16, v66, -v87
	v_mul_f32_e32 v88, s60, v88
	v_mul_f32_e32 v89, s60, v89
	v_mul_f32_e32 v90, s60, v90
	v_mul_f32_e32 v91, s60, v91
	v_fma_f32 v1, v1, v72, -v88
	v_fma_f32 v49, v49, v72, -v89
	v_fma_f32 v33, v33, v72, -v90
	v_fma_f32 v17, v17, v72, -v91
	v_mul_f32_e32 v92, s60, v92
	v_mul_f32_e32 v93, s60, v93
	v_mul_f32_e32 v94, s60, v94
	v_mul_f32_e32 v95, s60, v95
	v_fma_f32 v2, v2, v73, -v92
	v_fma_f32 v50, v50, v73, -v93
	v_fma_f32 v34, v34, v73, -v94
	v_fma_f32 v18, v18, v73, -v95
	v_mul_f32_e32 v96, s60, v96
	v_mul_f32_e32 v97, s60, v97
	v_mul_f32_e32 v98, s60, v98
	v_mul_f32_e32 v99, s60, v99
	v_fma_f32 v3, v3, v74, -v96
	v_fma_f32 v51, v51, v74, -v97
	v_fma_f32 v35, v35, v74, -v98
	v_fma_f32 v19, v19, v74, -v99
	v_mul_f32_e32 v100, s60, v100
	v_mul_f32_e32 v101, s60, v101
	v_mul_f32_e32 v102, s60, v102
	v_mul_f32_e32 v103, s60, v103
	v_fma_f32 v4, v4, v75, -v100
	v_fma_f32 v52, v52, v75, -v101
	v_fma_f32 v36, v36, v75, -v102
	v_fma_f32 v20, v20, v75, -v103
	v_mul_f32_e32 v104, s60, v104
	v_mul_f32_e32 v105, s60, v105
	v_mul_f32_e32 v106, s60, v106
	v_mul_f32_e32 v107, s60, v107
	v_fma_f32 v5, v5, v77, -v104
	v_fma_f32 v53, v53, v77, -v105
	v_fma_f32 v37, v37, v77, -v106
	v_fma_f32 v21, v21, v77, -v107
	v_mul_f32_e32 v108, s60, v108
	v_mul_f32_e32 v109, s60, v109
	v_mul_f32_e32 v110, s60, v110
	v_mul_f32_e32 v111, s60, v111
	v_fma_f32 v6, v6, v78, -v108
	v_fma_f32 v54, v54, v78, -v109
	v_fma_f32 v38, v38, v78, -v110
	v_fma_f32 v22, v22, v78, -v111
	v_mul_f32_e32 v112, s60, v112
	v_mul_f32_e32 v113, s60, v113
	v_mul_f32_e32 v114, s60, v114
	v_mul_f32_e32 v115, s60, v115
	v_fma_f32 v7, v7, v80, -v112
	v_fma_f32 v55, v55, v80, -v113
	v_fma_f32 v39, v39, v80, -v114
	v_fma_f32 v23, v23, v80, -v115
	v_mul_f32_e32 v116, s60, v116
	v_mul_f32_e32 v117, s60, v117
	v_mul_f32_e32 v118, s60, v118
	v_mul_f32_e32 v119, s60, v119
	v_fma_f32 v8, v8, v81, -v116
	v_fma_f32 v56, v56, v81, -v117
	v_fma_f32 v40, v40, v81, -v118
	v_fma_f32 v24, v24, v81, -v119
	v_mul_f32_e32 v120, s60, v120
	v_mul_f32_e32 v121, s60, v121
	v_mul_f32_e32 v122, s60, v122
	v_mul_f32_e32 v123, s60, v123
	v_fma_f32 v9, v9, v83, -v120
	v_fma_f32 v57, v57, v83, -v121
	v_fma_f32 v41, v41, v83, -v122
	v_fma_f32 v25, v25, v83, -v123
	v_mul_f32_e32 v124, s60, v124
	v_mul_f32_e32 v125, s60, v125
	v_mul_f32_e32 v126, s60, v126
	v_mul_f32_e32 v127, s60, v127
	v_fma_f32 v10, v10, v82, -v124
	v_fma_f32 v58, v58, v82, -v125
	v_fma_f32 v42, v42, v82, -v126
	v_fma_f32 v26, v26, v82, -v127
	v_mul_f32_e32 v128, s60, v128
	v_mul_f32_e32 v129, s60, v129
	v_mul_f32_e32 v130, s60, v130
	v_mul_f32_e32 v131, s60, v131
	v_fma_f32 v11, v11, v79, -v128
	v_fma_f32 v59, v59, v79, -v129
	v_fma_f32 v43, v43, v79, -v130
	v_fma_f32 v27, v27, v79, -v131
	v_mul_f32_e32 v132, s60, v132
	v_mul_f32_e32 v133, s60, v133
	v_mul_f32_e32 v134, s60, v134
	v_mul_f32_e32 v135, s60, v135
	v_fma_f32 v12, v12, v76, -v132
	v_fma_f32 v60, v60, v76, -v133
	v_fma_f32 v44, v44, v76, -v134
; __device__ __forceinline__ int crow(int r, int hi) { return (r & 3) + 8 * (r >> 2) + 4 * hi; }
; template <int MODE, int ORD> ...
;     ...
;       for (int r = 0; r < 16; ++r) { const int orow = crow(r, hi); float s = 0.f;
; #pragma unroll
;         for (int d0 = 0; d0 < 4; ++d0) { const float v = o[d0][r] * rli[r] - lam * X[orow * 128 + d0 * 32 + r32]; o[d0][r] = v; s = fmaf(v, v, s); }
;         ssq[r] = s; }
; #pragma unroll
;       for (int r = 0; r < 16; ++r) {
; #pragma unroll
;         for (int off = 1; off < 32; off <<= 1) ssq[r] += __shfl_xor(ssq[r], off);
;       }
	v_fma_f32 v28, v28, v76, -v135
	v_mul_f32_e32 v136, s60, v136
	v_mul_f32_e32 v137, s60, v137
	v_mul_f32_e32 v138, s60, v138
	v_mul_f32_e32 v139, s60, v139
	v_fma_f32 v13, v13, v71, -v136
	v_fma_f32 v61, v61, v71, -v137
	v_fma_f32 v45, v45, v71, -v138
	v_fma_f32 v29, v29, v71, -v139
	v_mul_f32_e32 v140, s60, v140
	v_mul_f32_e32 v141, s60, v141
	v_mul_f32_e32 v142, s60, v142
	v_mul_f32_e32 v143, s60, v143
	v_fma_f32 v14, v14, v68, -v140
	v_fma_f32 v62, v62, v68, -v141
	v_fma_f32 v46, v46, v68, -v142
	v_fma_f32 v30, v30, v68, -v143
	v_mul_f32_e32 v144, s60, v144
	v_mul_f32_e32 v145, s60, v145
	v_mul_f32_e32 v146, s60, v146
	v_mul_f32_e32 v147, s60, v147
	v_fma_f32 v15, v15, v69, -v144
	v_fma_f32 v63, v63, v69, -v145
	v_fma_f32 v47, v47, v69, -v146
	v_fma_f32 v31, v31, v69, -v147
	v_mul_f32_e32 v148, v0, v0
	v_mul_f32_e32 v149, v1, v1
	v_mul_f32_e32 v150, v2, v2
	v_mul_f32_e32 v151, v3, v3
	v_mul_f32_e32 v152, v4, v4
	v_mul_f32_e32 v153, v5, v5
	v_mul_f32_e32 v154, v6, v6
	v_mul_f32_e32 v155, v7, v7
	v_mul_f32_e32 v156, v8, v8
	v_mul_f32_e32 v157, v9, v9
	v_mul_f32_e32 v158, v10, v10
	v_mul_f32_e32 v159, v11, v11
	v_mul_f32_e32 v160, v12, v12
	v_mul_f32_e32 v161, v13, v13
	v_mul_f32_e32 v162, v14, v14
	v_mul_f32_e32 v163, v15, v15
	v_fmac_f32_e32 v148, v48, v48
	v_fmac_f32_e32 v149, v49, v49
	v_fmac_f32_e32 v150, v50, v50
	v_fmac_f32_e32 v151, v51, v51
	v_fmac_f32_e32 v152, v52, v52
	v_fmac_f32_e32 v153, v53, v53
	v_fmac_f32_e32 v154, v54, v54
	v_fmac_f32_e32 v155, v55, v55
	v_fmac_f32_e32 v156, v56, v56
	v_fmac_f32_e32 v157, v57, v57
	v_fmac_f32_e32 v158, v58, v58
	v_fmac_f32_e32 v159, v59, v59
	v_fmac_f32_e32 v160, v60, v60
	v_fmac_f32_e32 v161, v61, v61
	v_fmac_f32_e32 v162, v62, v62
	v_fmac_f32_e32 v163, v63, v63
	v_fmac_f32_e32 v148, v32, v32
	v_fmac_f32_e32 v149, v33, v33
	v_fmac_f32_e32 v150, v34, v34
	v_fmac_f32_e32 v151, v35, v35
	v_fmac_f32_e32 v152, v36, v36
	v_fmac_f32_e32 v153, v37, v37
	v_fmac_f32_e32 v154, v38, v38
	v_fmac_f32_e32 v155, v39, v39
	v_fmac_f32_e32 v156, v40, v40
	v_fmac_f32_e32 v157, v41, v41
	v_fmac_f32_e32 v158, v42, v42
	v_fmac_f32_e32 v159, v43, v43
	v_fmac_f32_e32 v160, v44, v44
	v_fmac_f32_e32 v161, v45, v45
	v_fmac_f32_e32 v162, v46, v46
	v_fmac_f32_e32 v163, v47, v47
	v_fmac_f32_e32 v148, v16, v16
	v_fmac_f32_e32 v149, v17, v17
	v_fmac_f32_e32 v150, v18, v18
	v_fmac_f32_e32 v151, v19, v19
	v_fmac_f32_e32 v152, v20, v20
	v_fmac_f32_e32 v153, v21, v21
	v_fmac_f32_e32 v154, v22, v22
	v_fmac_f32_e32 v155, v23, v23
	v_fmac_f32_e32 v156, v24, v24
	v_fmac_f32_e32 v157, v25, v25
	v_fmac_f32_e32 v158, v26, v26
	v_fmac_f32_e32 v159, v27, v27
	v_fmac_f32_e32 v160, v28, v28
	v_fmac_f32_e32 v161, v29, v29
	v_fmac_f32_e32 v162, v30, v30
	v_fmac_f32_e32 v163, v31, v31
	v_add_f32_dpp v148, v148, v148 quad_perm:[1,0,3,2] row_mask:0xf bank_mask:0xf
	v_add_f32_dpp v149, v149, v149 quad_perm:[1,0,3,2] row_mask:0xf bank_mask:0xf
	v_add_f32_dpp v150, v150, v150 quad_perm:[1,0,3,2] row_mask:0xf bank_mask:0xf
	v_add_f32_dpp v151, v151, v151 quad_perm:[1,0,3,2] row_mask:0xf bank_mask:0xf
	v_add_f32_dpp v152, v152, v152 quad_perm:[1,0,3,2] row_mask:0xf bank_mask:0xf
	v_add_f32_dpp v153, v153, v153 quad_perm:[1,0,3,2] row_mask:0xf bank_mask:0xf
	v_add_f32_dpp v154, v154, v154 quad_perm:[1,0,3,2] row_mask:0xf bank_mask:0xf
	v_add_f32_dpp v155, v155, v155 quad_perm:[1,0,3,2] row_mask:0xf bank_mask:0xf
	v_add_f32_dpp v156, v156, v156 quad_perm:[1,0,3,2] row_mask:0xf bank_mask:0xf
	v_add_f32_dpp v157, v157, v157 quad_perm:[1,0,3,2] row_mask:0xf bank_mask:0xf
	v_add_f32_dpp v158, v158, v158 quad_perm:[1,0,3,2] row_mask:0xf bank_mask:0xf
	v_add_f32_dpp v159, v159, v159 quad_perm:[1,0,3,2] row_mask:0xf bank_mask:0xf
	v_add_f32_dpp v160, v160, v160 quad_perm:[1,0,3,2] row_mask:0xf bank_mask:0xf
	v_add_f32_dpp v161, v161, v161 quad_perm:[1,0,3,2] row_mask:0xf bank_mask:0xf
	v_add_f32_dpp v162, v162, v162 quad_perm:[1,0,3,2] row_mask:0xf bank_mask:0xf
	v_add_f32_dpp v163, v163, v163 quad_perm:[1,0,3,2] row_mask:0xf bank_mask:0xf
	v_add_f32_dpp v148, v148, v148 quad_perm:[2,3,0,1] row_mask:0xf bank_mask:0xf
	v_add_f32_dpp v149, v149, v149 quad_perm:[2,3,0,1] row_mask:0xf bank_mask:0xf
	v_add_f32_dpp v150, v150, v150 quad_perm:[2,3,0,1] row_mask:0xf bank_mask:0xf
	v_add_f32_dpp v151, v151, v151 quad_perm:[2,3,0,1] row_mask:0xf bank_mask:0xf
	v_add_f32_dpp v152, v152, v152 quad_perm:[2,3,0,1] row_mask:0xf bank_mask:0xf
	v_add_f32_dpp v153, v153, v153 quad_perm:[2,3,0,1] row_mask:0xf bank_mask:0xf
	v_add_f32_dpp v154, v154, v154 quad_perm:[2,3,0,1] row_mask:0xf bank_mask:0xf
	v_add_f32_dpp v155, v155, v155 quad_perm:[2,3,0,1] row_mask:0xf bank_mask:0xf
	v_add_f32_dpp v156, v156, v156 quad_perm:[2,3,0,1] row_mask:0xf bank_mask:0xf
	v_add_f32_dpp v157, v157, v157 quad_perm:[2,3,0,1] row_mask:0xf bank_mask:0xf
	v_add_f32_dpp v158, v158, v158 quad_perm:[2,3,0,1] row_mask:0xf bank_mask:0xf
	v_add_f32_dpp v159, v159, v159 quad_perm:[2,3,0,1] row_mask:0xf bank_mask:0xf
	v_add_f32_dpp v160, v160, v160 quad_perm:[2,3,0,1] row_mask:0xf bank_mask:0xf
	v_add_f32_dpp v161, v161, v161 quad_perm:[2,3,0,1] row_mask:0xf bank_mask:0xf
	v_add_f32_dpp v162, v162, v162 quad_perm:[2,3,0,1] row_mask:0xf bank_mask:0xf
	v_add_f32_dpp v163, v163, v163 quad_perm:[2,3,0,1] row_mask:0xf bank_mask:0xf
	v_add_f32_dpp v148, v148, v148 row_half_mirror row_mask:0xf bank_mask:0xf
	v_add_f32_dpp v149, v149, v149 row_half_mirror row_mask:0xf bank_mask:0xf
	v_add_f32_dpp v150, v150, v150 row_half_mirror row_mask:0xf bank_mask:0xf
	v_add_f32_dpp v151, v151, v151 row_half_mirror row_mask:0xf bank_mask:0xf
	v_add_f32_dpp v152, v152, v152 row_half_mirror row_mask:0xf bank_mask:0xf
; __device__ __forceinline__ int crow(int r, int hi) { return (r & 3) + 8 * (r >> 2) + 4 * hi; }
; template <int MODE, int ORD> ...
;     ...
;       for (int r = 0; r < 16; ++r) {
; #pragma unroll
;         for (int off = 1; off < 32; off <<= 1) ssq[r] += __shfl_xor(ssq[r], off);
;       }
;       float gg[4];
; #pragma unroll
;       for (int d0 = 0; d0 < 4; ++d0) gg[d0] = subg[d0 * 32 + r32] * oscale;
;       bf16* Ow = Ob + (long)(wq * 32) * LDO;
; #pragma unroll
;       for (int r = 0; r < 16; ++r) { const int orow = crow(r, hi); const float rs = __builtin_amdgcn_rsqf(ssq[r] * (1.f / 128.f) + 1e-6f);
	v_add_f32_dpp v153, v153, v153 row_half_mirror row_mask:0xf bank_mask:0xf
	v_add_f32_dpp v154, v154, v154 row_half_mirror row_mask:0xf bank_mask:0xf
	v_add_f32_dpp v155, v155, v155 row_half_mirror row_mask:0xf bank_mask:0xf
	v_add_f32_dpp v156, v156, v156 row_half_mirror row_mask:0xf bank_mask:0xf
	v_add_f32_dpp v157, v157, v157 row_half_mirror row_mask:0xf bank_mask:0xf
	v_add_f32_dpp v158, v158, v158 row_half_mirror row_mask:0xf bank_mask:0xf
	v_add_f32_dpp v159, v159, v159 row_half_mirror row_mask:0xf bank_mask:0xf
	v_add_f32_dpp v160, v160, v160 row_half_mirror row_mask:0xf bank_mask:0xf
	v_add_f32_dpp v161, v161, v161 row_half_mirror row_mask:0xf bank_mask:0xf
	v_add_f32_dpp v162, v162, v162 row_half_mirror row_mask:0xf bank_mask:0xf
	v_add_f32_dpp v163, v163, v163 row_half_mirror row_mask:0xf bank_mask:0xf
	v_add_f32_dpp v148, v148, v148 row_mirror row_mask:0xf bank_mask:0xf
	v_add_f32_dpp v149, v149, v149 row_mirror row_mask:0xf bank_mask:0xf
	v_add_f32_dpp v150, v150, v150 row_mirror row_mask:0xf bank_mask:0xf
	v_add_f32_dpp v151, v151, v151 row_mirror row_mask:0xf bank_mask:0xf
	v_add_f32_dpp v152, v152, v152 row_mirror row_mask:0xf bank_mask:0xf
	v_add_f32_dpp v153, v153, v153 row_mirror row_mask:0xf bank_mask:0xf
	v_add_f32_dpp v154, v154, v154 row_mirror row_mask:0xf bank_mask:0xf
	v_add_f32_dpp v155, v155, v155 row_mirror row_mask:0xf bank_mask:0xf
	v_add_f32_dpp v156, v156, v156 row_mirror row_mask:0xf bank_mask:0xf
	v_add_f32_dpp v157, v157, v157 row_mirror row_mask:0xf bank_mask:0xf
	v_add_f32_dpp v158, v158, v158 row_mirror row_mask:0xf bank_mask:0xf
	v_add_f32_dpp v159, v159, v159 row_mirror row_mask:0xf bank_mask:0xf
	v_add_f32_dpp v160, v160, v160 row_mirror row_mask:0xf bank_mask:0xf
	v_add_f32_dpp v161, v161, v161 row_mirror row_mask:0xf bank_mask:0xf
	v_add_f32_dpp v162, v162, v162 row_mirror row_mask:0xf bank_mask:0xf
	v_add_f32_dpp v163, v163, v163 row_mirror row_mask:0xf bank_mask:0xf
	v_mov_b32_e32 v84, v148
	v_mov_b32_e32 v85, v149
	v_mov_b32_e32 v86, v150
	v_mov_b32_e32 v87, v151
	v_mov_b32_e32 v88, v152
	v_mov_b32_e32 v89, v153
	v_mov_b32_e32 v90, v154
	v_mov_b32_e32 v91, v155
	v_mov_b32_e32 v92, v156
	v_mov_b32_e32 v93, v157
	v_mov_b32_e32 v94, v158
	v_mov_b32_e32 v95, v159
	v_mov_b32_e32 v96, v160
	v_mov_b32_e32 v97, v161
	v_mov_b32_e32 v98, v162
	v_mov_b32_e32 v99, v163
	v_permlane16_swap_b32_e32 v84, v148
	v_permlane16_swap_b32_e32 v85, v149
	v_permlane16_swap_b32_e32 v86, v150
	v_permlane16_swap_b32_e32 v87, v151
	v_permlane16_swap_b32_e32 v88, v152
	v_permlane16_swap_b32_e32 v89, v153
	v_permlane16_swap_b32_e32 v90, v154
	v_permlane16_swap_b32_e32 v91, v155
	v_permlane16_swap_b32_e32 v92, v156
	v_permlane16_swap_b32_e32 v93, v157
	v_permlane16_swap_b32_e32 v94, v158
	v_permlane16_swap_b32_e32 v95, v159
	v_permlane16_swap_b32_e32 v96, v160
	v_permlane16_swap_b32_e32 v97, v161
	v_permlane16_swap_b32_e32 v98, v162
	v_permlane16_swap_b32_e32 v99, v163
	v_add_f32_e32 v148, v148, v84
	v_add_f32_e32 v149, v149, v85
	v_add_f32_e32 v150, v150, v86
	v_add_f32_e32 v151, v151, v87
	v_add_f32_e32 v152, v152, v88
	v_add_f32_e32 v153, v153, v89
	v_add_f32_e32 v154, v154, v90
	v_add_f32_e32 v155, v155, v91
	v_add_f32_e32 v156, v156, v92
	v_add_f32_e32 v157, v157, v93
	v_add_f32_e32 v158, v158, v94
	v_add_f32_e32 v159, v159, v95
	v_add_f32_e32 v160, v160, v96
	v_add_f32_e32 v161, v161, v97
	v_add_f32_e32 v162, v162, v98
	v_add_f32_e32 v163, v163, v99
	v_fmamk_f32 v148, v148, 0x3c000000, v239
	v_fmamk_f32 v149, v149, 0x3c000000, v239
	v_fmamk_f32 v150, v150, 0x3c000000, v239
	v_fmamk_f32 v151, v151, 0x3c000000, v239
	v_fmamk_f32 v152, v152, 0x3c000000, v239
	v_fmamk_f32 v153, v153, 0x3c000000, v239
	v_fmamk_f32 v154, v154, 0x3c000000, v239
	v_fmamk_f32 v155, v155, 0x3c000000, v239
	v_fmamk_f32 v156, v156, 0x3c000000, v239
	v_fmamk_f32 v157, v157, 0x3c000000, v239
	v_fmamk_f32 v158, v158, 0x3c000000, v239
	v_fmamk_f32 v159, v159, 0x3c000000, v239
	v_fmamk_f32 v160, v160, 0x3c000000, v239
	v_fmamk_f32 v161, v161, 0x3c000000, v239
	v_fmamk_f32 v162, v162, 0x3c000000, v239
	v_fmamk_f32 v163, v163, 0x3c000000, v239
	v_rsq_f32_e32 v148, v148
	v_rsq_f32_e32 v149, v149
	v_rsq_f32_e32 v150, v150
	v_rsq_f32_e32 v151, v151
	v_rsq_f32_e32 v152, v152
	v_rsq_f32_e32 v153, v153
	v_rsq_f32_e32 v154, v154
	v_rsq_f32_e32 v155, v155
	v_rsq_f32_e32 v156, v156
	v_rsq_f32_e32 v157, v157
	v_rsq_f32_e32 v158, v158
	v_rsq_f32_e32 v159, v159
	v_rsq_f32_e32 v160, v160
	v_rsq_f32_e32 v161, v161
	v_rsq_f32_e32 v162, v162
	v_rsq_f32_e32 v163, v163
	s_waitcnt vmcnt(0)
; __device__ __forceinline__ int crow(int r, int hi) { return (r & 3) + 8 * (r >> 2) + 4 * hi; }
; template <int MODE, int ORD> ...
;     ...
;       float gg[4];
; #pragma unroll
;       for (int d0 = 0; d0 < 4; ++d0) gg[d0] = subg[d0 * 32 + r32] * oscale;
;       bf16* Ow = Ob + (long)(wq * 32) * LDO;
; #pragma unroll
;       for (int r = 0; r < 16; ++r) { const int orow = crow(r, hi); const float rs = __builtin_amdgcn_rsqf(ssq[r] * (1.f / 128.f) + 1e-6f);
; #pragma unroll
;         for (int d0 = 0; d0 < 4; ++d0) { __hip_bfloat16 bv = __float2bfloat16(o[d0][r] * rs * gg[d0]); Ow[(long)orow * LDO + d0 * 32 + r32] = *reinterpret_cast<bf16*>(&bv); } }
	v_mul_f32_e32 v164, v183, v164
	v_mul_f32_e32 v165, v183, v165
	v_mul_f32_e32 v166, v183, v166
	v_mul_f32_e32 v167, v183, v167
	s_lshl_b32 s6, s66, 14
	v_lshlrev_b32_e32 v168, 1, v184
	v_lshl_add_u32 v168, v185, 10, v168
	v_add_u32_e32 v168, s6, v168
	v_mul_f32_e32 v0, v0, v148
	v_mul_f32_e32 v48, v48, v148
	v_mul_f32_e32 v32, v32, v148
	v_mul_f32_e32 v16, v16, v148
	v_mul_f32_e32 v0, v0, v164
	v_mul_f32_e32 v48, v48, v165
	v_mul_f32_e32 v32, v32, v166
	v_mul_f32_e32 v16, v16, v167
	v_cvt_pk_bf16_f32 v0, v0, v0
	v_cvt_pk_bf16_f32 v48, v48, v48
	v_cvt_pk_bf16_f32 v32, v32, v32
	v_cvt_pk_bf16_f32 v16, v16, v16
	ds_write_b16 v168, v0
	ds_write_b16 v168, v48 offset:64
	ds_write_b16 v168, v32 offset:128
	ds_write_b16 v168, v16 offset:192
	v_mul_f32_e32 v1, v1, v149
	v_mul_f32_e32 v49, v49, v149
	v_mul_f32_e32 v33, v33, v149
	v_mul_f32_e32 v17, v17, v149
	v_mul_f32_e32 v1, v1, v164
	v_mul_f32_e32 v49, v49, v165
	v_mul_f32_e32 v33, v33, v166
	v_mul_f32_e32 v17, v17, v167
	v_cvt_pk_bf16_f32 v1, v1, v1
	v_cvt_pk_bf16_f32 v49, v49, v49
	v_cvt_pk_bf16_f32 v33, v33, v33
	v_cvt_pk_bf16_f32 v17, v17, v17
	ds_write_b16 v168, v1 offset:256
	ds_write_b16 v168, v49 offset:320
	ds_write_b16 v168, v33 offset:384
	ds_write_b16 v168, v17 offset:448
	v_mul_f32_e32 v2, v2, v150
	v_mul_f32_e32 v50, v50, v150
	v_mul_f32_e32 v34, v34, v150
	v_mul_f32_e32 v18, v18, v150
	v_mul_f32_e32 v2, v2, v164
	v_mul_f32_e32 v50, v50, v165
	v_mul_f32_e32 v34, v34, v166
	v_mul_f32_e32 v18, v18, v167
	v_cvt_pk_bf16_f32 v2, v2, v2
	v_cvt_pk_bf16_f32 v50, v50, v50
	v_cvt_pk_bf16_f32 v34, v34, v34
	v_cvt_pk_bf16_f32 v18, v18, v18
	ds_write_b16 v168, v2 offset:512
	ds_write_b16 v168, v50 offset:576
	ds_write_b16 v168, v34 offset:640
	ds_write_b16 v168, v18 offset:704
	v_mul_f32_e32 v3, v3, v151
	v_mul_f32_e32 v51, v51, v151
	v_mul_f32_e32 v35, v35, v151
	v_mul_f32_e32 v19, v19, v151
	v_mul_f32_e32 v3, v3, v164
	v_mul_f32_e32 v51, v51, v165
	v_mul_f32_e32 v35, v35, v166
	v_mul_f32_e32 v19, v19, v167
	v_cvt_pk_bf16_f32 v3, v3, v3
	v_cvt_pk_bf16_f32 v51, v51, v51
	v_cvt_pk_bf16_f32 v35, v35, v35
	v_cvt_pk_bf16_f32 v19, v19, v19
	ds_write_b16 v168, v3 offset:768
	ds_write_b16 v168, v51 offset:832
	ds_write_b16 v168, v35 offset:896
	ds_write_b16 v168, v19 offset:960
	v_mul_f32_e32 v4, v4, v152
	v_mul_f32_e32 v52, v52, v152
	v_mul_f32_e32 v36, v36, v152
	v_mul_f32_e32 v20, v20, v152
	v_mul_f32_e32 v4, v4, v164
	v_mul_f32_e32 v52, v52, v165
	v_mul_f32_e32 v36, v36, v166
	v_mul_f32_e32 v20, v20, v167
	v_cvt_pk_bf16_f32 v4, v4, v4
	v_cvt_pk_bf16_f32 v52, v52, v52
	v_cvt_pk_bf16_f32 v36, v36, v36
	v_cvt_pk_bf16_f32 v20, v20, v20
	ds_write_b16 v168, v4 offset:2048
	ds_write_b16 v168, v52 offset:2112
	ds_write_b16 v168, v36 offset:2176
	ds_write_b16 v168, v20 offset:2240
	v_mul_f32_e32 v5, v5, v153
	v_mul_f32_e32 v53, v53, v153
	v_mul_f32_e32 v37, v37, v153
	v_mul_f32_e32 v21, v21, v153
	v_mul_f32_e32 v5, v5, v164
	v_mul_f32_e32 v53, v53, v165
	v_mul_f32_e32 v37, v37, v166
	v_mul_f32_e32 v21, v21, v167
	v_cvt_pk_bf16_f32 v5, v5, v5
	v_cvt_pk_bf16_f32 v53, v53, v53
	v_cvt_pk_bf16_f32 v37, v37, v37
	v_cvt_pk_bf16_f32 v21, v21, v21
	ds_write_b16 v168, v5 offset:2304
	ds_write_b16 v168, v53 offset:2368
	ds_write_b16 v168, v37 offset:2432
	ds_write_b16 v168, v21 offset:2496
	v_mul_f32_e32 v6, v6, v154
	v_mul_f32_e32 v54, v54, v154
	v_mul_f32_e32 v38, v38, v154
	v_mul_f32_e32 v22, v22, v154
	v_mul_f32_e32 v6, v6, v164
	v_mul_f32_e32 v54, v54, v165
	v_mul_f32_e32 v38, v38, v166
	v_mul_f32_e32 v22, v22, v167
	v_cvt_pk_bf16_f32 v6, v6, v6
	v_cvt_pk_bf16_f32 v54, v54, v54
	v_cvt_pk_bf16_f32 v38, v38, v38
	v_cvt_pk_bf16_f32 v22, v22, v22
	ds_write_b16 v168, v6 offset:2560
	ds_write_b16 v168, v54 offset:2624
	ds_write_b16 v168, v38 offset:2688
	ds_write_b16 v168, v22 offset:2752
	v_mul_f32_e32 v7, v7, v155
	v_mul_f32_e32 v55, v55, v155
	v_mul_f32_e32 v39, v39, v155
	v_mul_f32_e32 v23, v23, v155
	v_mul_f32_e32 v7, v7, v164
	v_mul_f32_e32 v55, v55, v165
	v_mul_f32_e32 v39, v39, v166
	v_mul_f32_e32 v23, v23, v167
	v_cvt_pk_bf16_f32 v7, v7, v7
	v_cvt_pk_bf16_f32 v55, v55, v55
	v_cvt_pk_bf16_f32 v39, v39, v39
	v_cvt_pk_bf16_f32 v23, v23, v23
	ds_write_b16 v168, v7 offset:2816
	ds_write_b16 v168, v55 offset:2880
	ds_write_b16 v168, v39 offset:2944
	ds_write_b16 v168, v23 offset:3008
	v_mul_f32_e32 v8, v8, v156
	v_mul_f32_e32 v56, v56, v156
	v_mul_f32_e32 v40, v40, v156
	v_mul_f32_e32 v24, v24, v156
	v_mul_f32_e32 v8, v8, v164
	v_mul_f32_e32 v56, v56, v165
	v_mul_f32_e32 v40, v40, v166
	v_mul_f32_e32 v24, v24, v167
	v_cvt_pk_bf16_f32 v8, v8, v8
	v_cvt_pk_bf16_f32 v56, v56, v56
	v_cvt_pk_bf16_f32 v40, v40, v40
	v_cvt_pk_bf16_f32 v24, v24, v24
	ds_write_b16 v168, v8 offset:4096
	ds_write_b16 v168, v56 offset:4160
	ds_write_b16 v168, v40 offset:4224
	ds_write_b16 v168, v24 offset:4288
	v_mul_f32_e32 v9, v9, v157
	v_mul_f32_e32 v57, v57, v157
	v_mul_f32_e32 v41, v41, v157
	v_mul_f32_e32 v25, v25, v157
; __device__ __forceinline__ int crow(int r, int hi) { return (r & 3) + 8 * (r >> 2) + 4 * hi; }
; template <int MODE, int ORD> ...
;     ...
;       bf16* Ow = Ob + (long)(wq * 32) * LDO;
; #pragma unroll
;       for (int r = 0; r < 16; ++r) { const int orow = crow(r, hi); const float rs = __builtin_amdgcn_rsqf(ssq[r] * (1.f / 128.f) + 1e-6f);
; #pragma unroll
;         for (int d0 = 0; d0 < 4; ++d0) { __hip_bfloat16 bv = __float2bfloat16(o[d0][r] * rs * gg[d0]); Ow[(long)orow * LDO + d0 * 32 + r32] = *reinterpret_cast<bf16*>(&bv); } }
	v_mul_f32_e32 v9, v9, v164
	v_mul_f32_e32 v57, v57, v165
	v_mul_f32_e32 v41, v41, v166
	v_mul_f32_e32 v25, v25, v167
	v_cvt_pk_bf16_f32 v9, v9, v9
	v_cvt_pk_bf16_f32 v57, v57, v57
	v_cvt_pk_bf16_f32 v41, v41, v41
	v_cvt_pk_bf16_f32 v25, v25, v25
	ds_write_b16 v168, v9 offset:4352
	ds_write_b16 v168, v57 offset:4416
	ds_write_b16 v168, v41 offset:4480
	ds_write_b16 v168, v25 offset:4544
	v_mul_f32_e32 v10, v10, v158
	v_mul_f32_e32 v58, v58, v158
	v_mul_f32_e32 v42, v42, v158
	v_mul_f32_e32 v26, v26, v158
	v_mul_f32_e32 v10, v10, v164
	v_mul_f32_e32 v58, v58, v165
	v_mul_f32_e32 v42, v42, v166
	v_mul_f32_e32 v26, v26, v167
	v_cvt_pk_bf16_f32 v10, v10, v10
	v_cvt_pk_bf16_f32 v58, v58, v58
	v_cvt_pk_bf16_f32 v42, v42, v42
	v_cvt_pk_bf16_f32 v26, v26, v26
	ds_write_b16 v168, v10 offset:4608
	ds_write_b16 v168, v58 offset:4672
	ds_write_b16 v168, v42 offset:4736
	ds_write_b16 v168, v26 offset:4800
	v_mul_f32_e32 v11, v11, v159
	v_mul_f32_e32 v59, v59, v159
	v_mul_f32_e32 v43, v43, v159
	v_mul_f32_e32 v27, v27, v159
	v_mul_f32_e32 v11, v11, v164
	v_mul_f32_e32 v59, v59, v165
	v_mul_f32_e32 v43, v43, v166
	v_mul_f32_e32 v27, v27, v167
	v_cvt_pk_bf16_f32 v11, v11, v11
	v_cvt_pk_bf16_f32 v59, v59, v59
	v_cvt_pk_bf16_f32 v43, v43, v43
	v_cvt_pk_bf16_f32 v27, v27, v27
	ds_write_b16 v168, v11 offset:4864
	ds_write_b16 v168, v59 offset:4928
	ds_write_b16 v168, v43 offset:4992
	ds_write_b16 v168, v27 offset:5056
	v_mul_f32_e32 v12, v12, v160
	v_mul_f32_e32 v60, v60, v160
	v_mul_f32_e32 v44, v44, v160
	v_mul_f32_e32 v28, v28, v160
	v_mul_f32_e32 v12, v12, v164
	v_mul_f32_e32 v60, v60, v165
	v_mul_f32_e32 v44, v44, v166
	v_mul_f32_e32 v28, v28, v167
	v_cvt_pk_bf16_f32 v12, v12, v12
	v_cvt_pk_bf16_f32 v60, v60, v60
	v_cvt_pk_bf16_f32 v44, v44, v44
	v_cvt_pk_bf16_f32 v28, v28, v28
	ds_write_b16 v168, v12 offset:6144
	ds_write_b16 v168, v60 offset:6208
	ds_write_b16 v168, v44 offset:6272
	ds_write_b16 v168, v28 offset:6336
	v_mul_f32_e32 v13, v13, v161
	v_mul_f32_e32 v61, v61, v161
	v_mul_f32_e32 v45, v45, v161
	v_mul_f32_e32 v29, v29, v161
	v_mul_f32_e32 v13, v13, v164
	v_mul_f32_e32 v61, v61, v165
	v_mul_f32_e32 v45, v45, v166
	v_mul_f32_e32 v29, v29, v167
	v_cvt_pk_bf16_f32 v13, v13, v13
	v_cvt_pk_bf16_f32 v61, v61, v61
	v_cvt_pk_bf16_f32 v45, v45, v45
	v_cvt_pk_bf16_f32 v29, v29, v29
	ds_write_b16 v168, v13 offset:6400
	ds_write_b16 v168, v61 offset:6464
	ds_write_b16 v168, v45 offset:6528
	ds_write_b16 v168, v29 offset:6592
	v_mul_f32_e32 v14, v14, v162
	v_mul_f32_e32 v62, v62, v162
	v_mul_f32_e32 v46, v46, v162
	v_mul_f32_e32 v30, v30, v162
	v_mul_f32_e32 v14, v14, v164
	v_mul_f32_e32 v62, v62, v165
	v_mul_f32_e32 v46, v46, v166
	v_mul_f32_e32 v30, v30, v167
	v_cvt_pk_bf16_f32 v14, v14, v14
	v_cvt_pk_bf16_f32 v62, v62, v62
	v_cvt_pk_bf16_f32 v46, v46, v46
	v_cvt_pk_bf16_f32 v30, v30, v30
	ds_write_b16 v168, v14 offset:6656
	ds_write_b16 v168, v62 offset:6720
	ds_write_b16 v168, v46 offset:6784
	ds_write_b16 v168, v30 offset:6848
	v_mul_f32_e32 v15, v15, v163
	v_mul_f32_e32 v63, v63, v163
	v_mul_f32_e32 v47, v47, v163
	v_mul_f32_e32 v31, v31, v163
	v_mul_f32_e32 v15, v15, v164
	v_mul_f32_e32 v63, v63, v165
	v_mul_f32_e32 v47, v47, v166
	v_mul_f32_e32 v31, v31, v167
	v_cvt_pk_bf16_f32 v15, v15, v15
	v_cvt_pk_bf16_f32 v63, v63, v63
	v_cvt_pk_bf16_f32 v47, v47, v47
	v_cvt_pk_bf16_f32 v31, v31, v31
	ds_write_b16 v168, v15 offset:6912
	ds_write_b16 v168, v63 offset:6976
	ds_write_b16 v168, v47 offset:7040
	ds_write_b16 v168, v31 offset:7104
	v_lshl_or_b32 v169, v185, 5, v184
	v_lshl_add_u32 v170, v169, 4, s6
	v_lshrrev_b32_e32 v171, 4, v169
	v_and_b32_e32 v169, 15, v169
	v_lshlrev_b32_e32 v169, 4, v169
	v_lshl_or_b32 v169, v171, 12, v169
	s_waitcnt lgkmcnt(0)
	ds_read_b128 v[84:87], v170
	ds_read_b128 v[88:91], v170 offset:1024
	ds_read_b128 v[92:95], v170 offset:2048
	ds_read_b128 v[96:99], v170 offset:3072
	ds_read_b128 v[100:103], v170 offset:4096
	ds_read_b128 v[104:107], v170 offset:5120
	ds_read_b128 v[108:111], v170 offset:6144
	ds_read_b128 v[112:115], v170 offset:7168
	s_waitcnt lgkmcnt(7)
	global_store_dwordx4 v169, v[84:87], s[0:1]
	s_add_u32 s0, s0, 0x4000
	s_addc_u32 s1, s1, 0
	s_waitcnt lgkmcnt(6)
	global_store_dwordx4 v169, v[88:91], s[0:1]
	s_add_u32 s0, s0, 0x4000
	s_addc_u32 s1, s1, 0
	s_waitcnt lgkmcnt(5)
	global_store_dwordx4 v169, v[92:95], s[0:1]
	s_add_u32 s0, s0, 0x4000
	s_addc_u32 s1, s1, 0
	s_waitcnt lgkmcnt(4)
	global_store_dwordx4 v169, v[96:99], s[0:1]
	s_add_u32 s0, s0, 0x4000
	s_addc_u32 s1, s1, 0
	s_waitcnt lgkmcnt(3)
	global_store_dwordx4 v169, v[100:103], s[0:1]
	s_add_u32 s0, s0, 0x4000
	s_addc_u32 s1, s1, 0
	s_waitcnt lgkmcnt(2)
	global_store_dwordx4 v169, v[104:107], s[0:1]
	s_add_u32 s0, s0, 0x4000
	s_addc_u32 s1, s1, 0
	s_waitcnt lgkmcnt(1)
	global_store_dwordx4 v169, v[108:111], s[0:1]
	s_add_u32 s0, s0, 0x4000
	s_addc_u32 s1, s1, 0
	s_waitcnt lgkmcnt(0)
	global_store_dwordx4 v169, v[112:115], s[0:1]
	s_branch .LBB0_148
